# combine phase: hand-written token loop (6 SSD + 4 RWKV channels per lane, all 22 loads up front, consecutive tokens per wave)
# speedup vs baseline: 1.0163x; 1.0163x over previous
.Lcb7_entry:
	s_waitcnt vmcnt(0) lgkmcnt(0)
	v_readlane_b32 s98, v246, 10
	v_readlane_b32 s99, v246, 11
	s_nop 4
	v_and_b32_e32 v0, 63, v226
	v_mul_u32_u24_e32 v2, 12, v0
	v_mul_u32_u24_e32 v4, 24, v0
	v_lshlrev_b32_e32 v6, 3, v0
	v_lshlrev_b32_e32 v8, 4, v0
	v_mov_b32_e32 v3, 0
	v_mov_b32_e32 v5, 0
	v_mov_b32_e32 v7, 0
	v_mov_b32_e32 v9, 0
	s_load_dwordx2 s[100:101], s[98:99], 0x68
	s_waitcnt lgkmcnt(0)
	global_load_dwordx2 v[10:11], v4, s[100:101] offset:0
	global_load_dwordx2 v[12:13], v4, s[100:101] offset:8
	global_load_dwordx2 v[14:15], v4, s[100:101] offset:16
	s_load_dwordx2 s[100:101], s[98:99], 0x68
	s_waitcnt lgkmcnt(0)
	s_add_u32 s100, s100, 0xa00
	s_addc_u32 s101, s101, 0
	global_load_dwordx2 v[16:17], v4, s[100:101] offset:0
	global_load_dwordx2 v[18:19], v4, s[100:101] offset:8
	global_load_dwordx2 v[20:21], v4, s[100:101] offset:16
	s_load_dwordx2 s[100:101], s[98:99], 0x68
	s_waitcnt lgkmcnt(0)
	s_add_u32 s100, s100, 0x1400
	s_addc_u32 s101, s101, 0
	global_load_dwordx2 v[22:23], v4, s[100:101] offset:0
	global_load_dwordx2 v[24:25], v4, s[100:101] offset:8
	global_load_dwordx2 v[26:27], v4, s[100:101] offset:16
	s_load_dwordx2 s[100:101], s[98:99], 0x68
	s_waitcnt lgkmcnt(0)
	s_add_u32 s100, s100, 0x1e00
	s_addc_u32 s101, s101, 0
	global_load_dwordx2 v[28:29], v4, s[100:101] offset:0
	global_load_dwordx2 v[30:31], v4, s[100:101] offset:8
	global_load_dwordx2 v[32:33], v4, s[100:101] offset:16
	s_load_dwordx2 s[100:101], s[98:99], 0x68
	s_waitcnt lgkmcnt(0)
	s_add_u32 s100, s100, 0x2800
	s_addc_u32 s101, s101, 0
	global_load_dwordx2 v[34:35], v4, s[100:101] offset:0
	global_load_dwordx2 v[36:37], v4, s[100:101] offset:8
	global_load_dwordx2 v[38:39], v4, s[100:101] offset:16
	s_load_dwordx2 s[100:101], s[98:99], 0x70
	s_waitcnt lgkmcnt(0)
	global_load_dwordx2 v[40:41], v4, s[100:101] offset:0
	global_load_dwordx2 v[42:43], v4, s[100:101] offset:8
	global_load_dwordx2 v[44:45], v4, s[100:101] offset:16
	s_load_dwordx2 s[100:101], s[98:99], 0x90
	s_waitcnt lgkmcnt(0)
	global_load_dwordx2 v[46:47], v4, s[100:101] offset:0
	global_load_dwordx2 v[48:49], v4, s[100:101] offset:8
	global_load_dwordx2 v[50:51], v4, s[100:101] offset:16
	s_load_dwordx2 s[100:101], s[98:99], 0x88
	s_waitcnt lgkmcnt(0)
	v_mad_u32_u24 v236, v0, 6, 0
	v_lshrrev_b32_e32 v236, 6, v236
	v_lshlrev_b32_e32 v236, 2, v236
	global_load_dword v52, v236, s[100:101]
	v_mad_u32_u24 v236, v0, 6, 1
	v_lshrrev_b32_e32 v236, 6, v236
	v_lshlrev_b32_e32 v236, 2, v236
	global_load_dword v53, v236, s[100:101]
	v_mad_u32_u24 v236, v0, 6, 2
	v_lshrrev_b32_e32 v236, 6, v236
	v_lshlrev_b32_e32 v236, 2, v236
	global_load_dword v54, v236, s[100:101]
	v_mad_u32_u24 v236, v0, 6, 3
	v_lshrrev_b32_e32 v236, 6, v236
	v_lshlrev_b32_e32 v236, 2, v236
	global_load_dword v55, v236, s[100:101]
	v_mad_u32_u24 v236, v0, 6, 4
	v_lshrrev_b32_e32 v236, 6, v236
	v_lshlrev_b32_e32 v236, 2, v236
	global_load_dword v56, v236, s[100:101]
	v_mad_u32_u24 v236, v0, 6, 5
	v_lshrrev_b32_e32 v236, 6, v236
	v_lshlrev_b32_e32 v236, 2, v236
	global_load_dword v57, v236, s[100:101]
	s_load_dwordx2 s[100:101], s[98:99], 0x98
	s_waitcnt lgkmcnt(0)
	global_load_dwordx2 v[58:59], v8, s[100:101] offset:0
	global_load_dwordx2 v[60:61], v8, s[100:101] offset:8
	s_load_dwordx2 s[100:101], s[98:99], 0x98
	s_waitcnt lgkmcnt(0)
	s_add_u32 s100, s100, 0x400
	s_addc_u32 s101, s101, 0
	global_load_dwordx2 v[62:63], v8, s[100:101] offset:0
	global_load_dwordx2 v[64:65], v8, s[100:101] offset:8
	s_load_dwordx2 s[100:101], s[98:99], 0x98
	s_waitcnt lgkmcnt(0)
	s_add_u32 s100, s100, 0x800
	s_addc_u32 s101, s101, 0
	global_load_dwordx2 v[66:67], v8, s[100:101] offset:0
	global_load_dwordx2 v[68:69], v8, s[100:101] offset:8
	s_load_dwordx2 s[100:101], s[98:99], 0xd0
	s_waitcnt lgkmcnt(0)
	global_load_dwordx2 v[70:71], v8, s[100:101] offset:0
	global_load_dwordx2 v[72:73], v8, s[100:101] offset:8
	s_load_dwordx2 s[100:101], s[98:99], 0xd8
	s_waitcnt lgkmcnt(0)
	global_load_dwordx2 v[74:75], v8, s[100:101] offset:0
	global_load_dwordx2 v[76:77], v8, s[100:101] offset:8
	s_load_dwordx2 s[100:101], s[98:99], 0xe0
	s_waitcnt lgkmcnt(0)
	global_load_dwordx2 v[78:79], v8, s[100:101] offset:0
	global_load_dwordx2 v[80:81], v8, s[100:101] offset:8
	s_load_dwordx2 s[100:101], s[98:99], 0xe8
	s_waitcnt lgkmcnt(0)
	global_load_dwordx2 v[82:83], v8, s[100:101] offset:0
	global_load_dwordx2 v[84:85], v8, s[100:101] offset:8
	s_load_dwordx2 s[100:101], s[98:99], 0x178
	s_waitcnt lgkmcnt(0)
	v_mov_b32_e32 v86, s100
	v_mov_b32_e32 v87, s101
	v_lshl_add_u64 v[86:87], v[86:87], 0, v[2:3]
	s_load_dwordx2 s[100:101], s[98:99], 0x178
	s_waitcnt lgkmcnt(0)
	s_add_u32 s100, s100, 0xd20
	s_addc_u32 s101, s101, 0
	v_mov_b32_e32 v88, s100
	v_mov_b32_e32 v89, s101
	v_lshl_add_u64 v[88:89], v[88:89], 0, v[6:7]
	s_load_dwordx2 s[100:101], s[98:99], 0x198
	s_waitcnt lgkmcnt(0)
	v_mov_b32_e32 v90, s100
	v_mov_b32_e32 v91, s101
	v_lshl_add_u64 v[90:91], v[90:91], 0, v[2:3]
	s_load_dwordx2 s[100:101], s[98:99], 0x198
	s_waitcnt lgkmcnt(0)
	v_mov_b32_e32 v92, s100
	v_mov_b32_e32 v93, s101
	v_lshl_add_u64 v[92:93], v[92:93], 0, v[6:7]
	s_load_dwordx2 s[100:101], s[98:99], 0x188
	s_waitcnt lgkmcnt(0)
	v_mov_b32_e32 v94, s100
	v_mov_b32_e32 v95, s101
	v_lshl_add_u64 v[94:95], v[94:95], 0, v[6:7]
	v_mov_b32_e32 v1, 0x1520
	v_mov_b32_e32 v96, 0xa00
	v_mov_b32_e32 v98, 0xbfb8aa3b
	v_readfirstlane_b32 s6, v197
	s_waitcnt vmcnt(0)
	s_nop 3
	s_mov_b32 s20, s3
	s_movk_i32 s21, 0x5000
	s_cmp_eq_u32 s3, 0x800
	s_cbranch_scc0 .Lcb7_top
	s_mul_i32 s6, s6, 10
	s_mov_b32 s20, 1
	s_add_u32 s21, s6, 10
.Lcb7_top:
	s_cmp_lt_u32 s6, 0x1000
	s_movk_i32 s8, 0xfff
	s_cselect_b32 s8, 0xff, s8
	s_and_b32 s7, s6, s8
	s_mov_b32 s9, 0
	s_cmp_ge_u32 s7, 2
	s_cselect_b32 s10, 1, 0
	s_or_b32 s9, s9, s10
	s_cmp_ge_u32 s7, 1
	s_cselect_b32 s10, 2, 0
	s_or_b32 s9, s9, s10
	s_sub_u32 s11, s8, 1
	s_cmp_le_u32 s7, s11
	s_cselect_b32 s10, 8, 0
	s_or_b32 s9, s9, s10
	s_sub_u32 s11, s8, 2
	s_cmp_le_u32 s7, s11
	s_cselect_b32 s10, 16, 0
	s_or_b32 s9, s9, s10
	s_bitcmp1_b32 s9, 1
	s_cselect_b32 s10, 0.5, 0
	s_bitcmp1_b32 s9, 3
	s_cselect_b32 s11, 0.5, 0
	v_mov_b32_e32 v100, s10
	v_mov_b32_e32 v101, s11
	v_mov_b32_e32 v97, s6
	v_mad_u64_u32 v[106:107], vcc, v97, v1, v[86:87]
	global_load_dwordx3 v[118:120], v[106:107], off offset:2048
	global_load_dwordx3 v[130:132], v[106:107], off offset:1280
	s_bitcmp1_b32 s9, 0
	s_cselect_b32 s98, 0xffffd5c0, 0
	s_ashr_i32 s99, s98, 31
	v_lshl_add_u64 v[108:109], v[106:107], 0, s[98:99]
	global_load_dwordx3 v[110:112], v[108:109], off offset:2048
	s_bitcmp1_b32 s9, 1
	s_cselect_b32 s98, 0xffffeae0, 0
	s_ashr_i32 s99, s98, 31
	v_lshl_add_u64 v[108:109], v[106:107], 0, s[98:99]
	global_load_dwordx3 v[114:116], v[108:109], off offset:2048
	s_bitcmp1_b32 s9, 3
	s_cselect_b32 s98, 0x1520, 0
	s_ashr_i32 s99, s98, 31
	v_lshl_add_u64 v[108:109], v[106:107], 0, s[98:99]
	global_load_dwordx3 v[122:124], v[108:109], off offset:2048
	s_bitcmp1_b32 s9, 4
	s_cselect_b32 s98, 0x2a40, 0
	s_ashr_i32 s99, s98, 31
	v_lshl_add_u64 v[108:109], v[106:107], 0, s[98:99]
	global_load_dwordx3 v[126:128], v[108:109], off offset:2048
	v_mad_u64_u32 v[108:109], vcc, v97, v96, v[90:91]
	global_load_dwordx3 v[134:136], v[108:109], off offset:1024
	global_load_dwordx3 v[138:140], v[108:109], off offset:1792
	v_mad_u64_u32 v[108:109], vcc, v97, v96, v[92:93]
	global_load_dwordx2 v[142:143], v[108:109], off
	global_load_dwordx2 v[144:145], v[108:109], off offset:512
	v_mad_u64_u32 v[106:107], vcc, v97, v1, v[88:89]
	global_load_dwordx2 v[146:147], v[106:107], off offset:0
	global_load_dwordx2 v[152:153], v[106:107], off offset:512
	global_load_dwordx2 v[158:159], v[106:107], off offset:1024
	s_bitcmp1_b32 s9, 1
	s_cselect_b32 s98, 0xffffeae0, 0
	s_ashr_i32 s99, s98, 31
	v_lshl_add_u64 v[108:109], v[106:107], 0, s[98:99]
	global_load_dwordx2 v[148:149], v[108:109], off offset:0
	global_load_dwordx2 v[154:155], v[108:109], off offset:512
	global_load_dwordx2 v[160:161], v[108:109], off offset:1024
	s_bitcmp1_b32 s9, 3
	s_cselect_b32 s98, 0x1520, 0
	s_ashr_i32 s99, s98, 31
	v_lshl_add_u64 v[108:109], v[106:107], 0, s[98:99]
	global_load_dwordx2 v[150:151], v[108:109], off offset:0
	global_load_dwordx2 v[156:157], v[108:109], off offset:512
	global_load_dwordx2 v[162:163], v[108:109], off offset:1024
	v_mad_u64_u32 v[108:109], vcc, v97, v96, v[94:95]
	global_load_dwordx2 v[164:165], v[108:109], off offset:1024
	global_load_dwordx2 v[166:167], v[108:109], off offset:1536
	global_load_dwordx2 v[168:169], v[108:109], off offset:2048
	s_waitcnt vmcnt(14)
	v_pk_add_f32 v[170:171], v[40:41], 0 op_sel_hi:[1,0]
	v_pk_add_f32 v[172:173], v[42:43], 0 op_sel_hi:[1,0]
	v_pk_add_f32 v[174:175], v[44:45], 0 op_sel_hi:[1,0]
	s_bitcmp1_b32 s9, 0
	s_cbranch_scc0 .Lcb7_skip0
	v_lshlrev_b32_e32 v176, 16, v110
	v_and_b32_e32 v177, 0xffff0000, v110
	v_lshlrev_b32_e32 v178, 16, v111
	v_and_b32_e32 v179, 0xffff0000, v111
	v_lshlrev_b32_e32 v180, 16, v112
	v_and_b32_e32 v181, 0xffff0000, v112
	v_pk_fma_f32 v[170:171], v[10:11], v[176:177], v[170:171]
	v_pk_fma_f32 v[172:173], v[12:13], v[178:179], v[172:173]
	v_pk_fma_f32 v[174:175], v[14:15], v[180:181], v[174:175]
.Lcb7_skip0:
	s_bitcmp1_b32 s9, 1
	s_cbranch_scc0 .Lcb7_skip1
	v_lshlrev_b32_e32 v176, 16, v114
	v_and_b32_e32 v177, 0xffff0000, v114
	v_lshlrev_b32_e32 v178, 16, v115
	v_and_b32_e32 v179, 0xffff0000, v115
	v_lshlrev_b32_e32 v180, 16, v116
	v_and_b32_e32 v181, 0xffff0000, v116
	v_pk_fma_f32 v[170:171], v[16:17], v[176:177], v[170:171]
	v_pk_fma_f32 v[172:173], v[18:19], v[178:179], v[172:173]
	v_pk_fma_f32 v[174:175], v[20:21], v[180:181], v[174:175]
.Lcb7_skip1:
	v_lshlrev_b32_e32 v176, 16, v118
	v_and_b32_e32 v177, 0xffff0000, v118
	v_lshlrev_b32_e32 v178, 16, v119
	v_and_b32_e32 v179, 0xffff0000, v119
	v_lshlrev_b32_e32 v180, 16, v120
	v_and_b32_e32 v181, 0xffff0000, v120
	v_pk_fma_f32 v[170:171], v[22:23], v[176:177], v[170:171]
	v_pk_fma_f32 v[172:173], v[24:25], v[178:179], v[172:173]
	v_pk_fma_f32 v[174:175], v[26:27], v[180:181], v[174:175]
	s_bitcmp1_b32 s9, 3
	s_cbranch_scc0 .Lcb7_skip3
	v_lshlrev_b32_e32 v176, 16, v122
	v_and_b32_e32 v177, 0xffff0000, v122
	v_lshlrev_b32_e32 v178, 16, v123
	v_and_b32_e32 v179, 0xffff0000, v123
	v_lshlrev_b32_e32 v180, 16, v124
	v_and_b32_e32 v181, 0xffff0000, v124
	v_pk_fma_f32 v[170:171], v[28:29], v[176:177], v[170:171]
	v_pk_fma_f32 v[172:173], v[30:31], v[178:179], v[172:173]
	v_pk_fma_f32 v[174:175], v[32:33], v[180:181], v[174:175]
.Lcb7_skip3:
	s_bitcmp1_b32 s9, 4
	s_cbranch_scc0 .Lcb7_skip4
	v_lshlrev_b32_e32 v176, 16, v126
	v_and_b32_e32 v177, 0xffff0000, v126
	v_lshlrev_b32_e32 v178, 16, v127
	v_and_b32_e32 v179, 0xffff0000, v127
	v_lshlrev_b32_e32 v180, 16, v128
	v_and_b32_e32 v181, 0xffff0000, v128
	v_pk_fma_f32 v[170:171], v[34:35], v[176:177], v[170:171]
	v_pk_fma_f32 v[172:173], v[36:37], v[178:179], v[172:173]
	v_pk_fma_f32 v[174:175], v[38:39], v[180:181], v[174:175]
.Lcb7_skip4:
	v_pk_mul_f32 v[176:177], v[170:171], v[98:99] op_sel_hi:[1,0]
	v_pk_mul_f32 v[178:179], v[172:173], v[98:99] op_sel_hi:[1,0]
	v_pk_mul_f32 v[180:181], v[174:175], v[98:99] op_sel_hi:[1,0]
	v_exp_f32_e32 v176, v176
	v_exp_f32_e32 v177, v177
	v_exp_f32_e32 v178, v178
	v_exp_f32_e32 v179, v179
	v_exp_f32_e32 v180, v180
	v_exp_f32_e32 v181, v181
	v_pk_add_f32 v[176:177], v[176:177], 1.0 op_sel_hi:[1,0]
	v_pk_add_f32 v[178:179], v[178:179], 1.0 op_sel_hi:[1,0]
	v_pk_add_f32 v[180:181], v[180:181], 1.0 op_sel_hi:[1,0]
	v_rcp_f32_e32 v176, v176
	v_rcp_f32_e32 v177, v177
	v_rcp_f32_e32 v178, v178
	v_rcp_f32_e32 v179, v179
	v_rcp_f32_e32 v180, v180
	v_rcp_f32_e32 v181, v181
	v_pk_mul_f32 v[170:171], v[170:171], v[176:177]
	v_pk_mul_f32 v[172:173], v[172:173], v[178:179]
	v_pk_mul_f32 v[174:175], v[174:175], v[180:181]
	v_lshlrev_b32_e32 v182, 16, v130
	v_and_b32_e32 v183, 0xffff0000, v130
	v_lshlrev_b32_e32 v184, 16, v131
	v_and_b32_e32 v185, 0xffff0000, v131
	v_lshlrev_b32_e32 v186, 16, v132
	v_and_b32_e32 v187, 0xffff0000, v132
	v_pk_mul_f32 v[176:177], v[182:183], v[98:99] op_sel_hi:[1,0]
	v_pk_mul_f32 v[178:179], v[184:185], v[98:99] op_sel_hi:[1,0]
	v_pk_mul_f32 v[180:181], v[186:187], v[98:99] op_sel_hi:[1,0]
	v_exp_f32_e32 v176, v176
	v_exp_f32_e32 v177, v177
	v_exp_f32_e32 v178, v178
	v_exp_f32_e32 v179, v179
	v_exp_f32_e32 v180, v180
	v_exp_f32_e32 v181, v181
	v_pk_add_f32 v[176:177], v[176:177], 1.0 op_sel_hi:[1,0]
	v_pk_add_f32 v[178:179], v[178:179], 1.0 op_sel_hi:[1,0]
	v_pk_add_f32 v[180:181], v[180:181], 1.0 op_sel_hi:[1,0]
	v_rcp_f32_e32 v176, v176
	v_rcp_f32_e32 v177, v177
	v_rcp_f32_e32 v178, v178
	v_rcp_f32_e32 v179, v179
	v_rcp_f32_e32 v180, v180
	v_rcp_f32_e32 v181, v181
	v_pk_mul_f32 v[188:189], v[182:183], v[176:177]
	v_pk_mul_f32 v[190:191], v[184:185], v[178:179]
	v_pk_mul_f32 v[192:193], v[186:187], v[180:181]
	v_lshlrev_b32_e32 v176, 16, v134
	v_and_b32_e32 v177, 0xffff0000, v134
	v_lshlrev_b32_e32 v178, 16, v135
	v_and_b32_e32 v179, 0xffff0000, v135
	v_lshlrev_b32_e32 v180, 16, v136
	v_and_b32_e32 v181, 0xffff0000, v136
	v_lshlrev_b32_e32 v182, 16, v138
	v_and_b32_e32 v183, 0xffff0000, v138
	v_lshlrev_b32_e32 v184, 16, v139
	v_and_b32_e32 v185, 0xffff0000, v139
	v_lshlrev_b32_e32 v186, 16, v140
	v_and_b32_e32 v187, 0xffff0000, v140
	v_pk_add_f32 v[194:195], v[176:177], v[182:183]
	v_pk_add_f32 v[198:199], v[178:179], v[184:185]
	v_pk_add_f32 v[200:201], v[180:181], v[186:187]
	v_pk_fma_f32 v[194:195], v[52:53], v[170:171], v[194:195]
	v_pk_fma_f32 v[198:199], v[54:55], v[172:173], v[198:199]
	v_pk_fma_f32 v[200:201], v[56:57], v[174:175], v[200:201]
	v_pk_mul_f32 v[194:195], v[194:195], v[188:189]
	v_pk_mul_f32 v[198:199], v[198:199], v[190:191]
	v_pk_mul_f32 v[200:201], v[200:201], v[192:193]
	v_pk_mul_f32 v[238:239], v[194:195], v[194:195]
	v_pk_fma_f32 v[238:239], v[198:199], v[198:199], v[238:239]
	v_pk_fma_f32 v[238:239], v[200:201], v[200:201], v[238:239]
	v_add_f32_e32 v238, v238, v239
	s_waitcnt vmcnt(0)
	v_lshlrev_b32_e32 v202, 16, v142
	v_and_b32_e32 v203, 0xffff0000, v142
	v_lshlrev_b32_e32 v204, 16, v143
	v_and_b32_e32 v205, 0xffff0000, v143
	v_lshlrev_b32_e32 v218, 16, v144
	v_and_b32_e32 v219, 0xffff0000, v144
	v_lshlrev_b32_e32 v220, 16, v145
	v_and_b32_e32 v221, 0xffff0000, v145
	v_pk_add_f32 v[202:203], v[202:203], v[218:219]
	v_pk_add_f32 v[204:205], v[204:205], v[220:221]
	v_pk_add_f32 v[236:237], v[202:203], v[204:205]
	v_add_f32_e32 v236, v236, v237
	s_nop 1
	v_add_f32_dpp v236, v236, v236 row_ror:8 row_mask:0xf bank_mask:0xf bound_ctrl:1
	s_nop 1
	v_add_f32_dpp v236, v236, v236 row_ror:4 row_mask:0xf bank_mask:0xf bound_ctrl:1
	s_nop 1
	v_add_f32_dpp v236, v236, v236 row_ror:2 row_mask:0xf bank_mask:0xf bound_ctrl:1
	s_nop 1
	v_add_f32_dpp v236, v236, v236 row_ror:1 row_mask:0xf bank_mask:0xf bound_ctrl:1
	v_mul_f32_e32 v102, 0x3c800000, v236
	v_pk_add_f32 v[202:203], v[202:203], v[102:103] op_sel_hi:[1,0] neg_lo:[0,1] neg_hi:[0,1]
	v_pk_add_f32 v[204:205], v[204:205], v[102:103] op_sel_hi:[1,0] neg_lo:[0,1] neg_hi:[0,1]
	v_pk_mul_f32 v[236:237], v[202:203], v[202:203]
	v_pk_fma_f32 v[236:237], v[204:205], v[204:205], v[236:237]
	v_add_f32_e32 v236, v236, v237
	s_nop 1
	v_add_f32_dpp v236, v236, v236 row_ror:8 row_mask:0xf bank_mask:0xf bound_ctrl:1
	s_nop 1
	v_add_f32_dpp v236, v236, v236 row_ror:4 row_mask:0xf bank_mask:0xf bound_ctrl:1
	s_nop 1
	v_add_f32_dpp v236, v236, v236 row_ror:2 row_mask:0xf bank_mask:0xf bound_ctrl:1
	s_nop 1
	v_add_f32_dpp v236, v236, v236 row_ror:1 row_mask:0xf bank_mask:0xf bound_ctrl:1
	v_mov_b32_e32 v104, 0x3a27c5ac
	v_fmac_f32_e32 v104, 0x3c800000, v236
	v_rsq_f32_e32 v103, v104
	v_lshlrev_b32_e32 v218, 16, v146
	v_and_b32_e32 v219, 0xffff0000, v146
	v_lshlrev_b32_e32 v220, 16, v147
	v_and_b32_e32 v221, 0xffff0000, v147
	v_lshlrev_b32_e32 v222, 16, v148
	v_and_b32_e32 v223, 0xffff0000, v148
	v_lshlrev_b32_e32 v224, 16, v149
	v_and_b32_e32 v225, 0xffff0000, v149
	v_lshlrev_b32_e32 v228, 16, v150
	v_and_b32_e32 v229, 0xffff0000, v150
	v_lshlrev_b32_e32 v230, 16, v151
	v_and_b32_e32 v231, 0xffff0000, v151
	v_pk_mul_f32 v[222:223], v[222:223], v[100:101] op_sel_hi:[1,0]
	v_pk_mul_f32 v[224:225], v[224:225], v[100:101] op_sel_hi:[1,0]
	v_pk_fma_f32 v[222:223], v[228:229], v[100:101], v[222:223] op_sel:[0,1,0] op_sel_hi:[1,1,1]
	v_pk_fma_f32 v[224:225], v[230:231], v[100:101], v[224:225] op_sel:[0,1,0] op_sel_hi:[1,1,1]
	v_pk_add_f32 v[222:223], v[222:223], v[218:219] neg_lo:[0,1] neg_hi:[0,1]
	v_pk_add_f32 v[224:225], v[224:225], v[220:221] neg_lo:[0,1] neg_hi:[0,1]
	v_pk_fma_f32 v[206:207], v[58:59], v[222:223], v[218:219]
	v_pk_fma_f32 v[208:209], v[60:61], v[224:225], v[220:221]
	v_lshlrev_b32_e32 v218, 16, v152
	v_and_b32_e32 v219, 0xffff0000, v152
	v_lshlrev_b32_e32 v220, 16, v153
	v_and_b32_e32 v221, 0xffff0000, v153
	v_lshlrev_b32_e32 v222, 16, v154
	v_and_b32_e32 v223, 0xffff0000, v154
	v_lshlrev_b32_e32 v224, 16, v155
	v_and_b32_e32 v225, 0xffff0000, v155
	v_lshlrev_b32_e32 v228, 16, v156
	v_and_b32_e32 v229, 0xffff0000, v156
	v_lshlrev_b32_e32 v230, 16, v157
	v_and_b32_e32 v231, 0xffff0000, v157
	v_pk_mul_f32 v[222:223], v[222:223], v[100:101] op_sel_hi:[1,0]
	v_pk_mul_f32 v[224:225], v[224:225], v[100:101] op_sel_hi:[1,0]
	v_pk_fma_f32 v[222:223], v[228:229], v[100:101], v[222:223] op_sel:[0,1,0] op_sel_hi:[1,1,1]
	v_pk_fma_f32 v[224:225], v[230:231], v[100:101], v[224:225] op_sel:[0,1,0] op_sel_hi:[1,1,1]
	v_pk_add_f32 v[222:223], v[222:223], v[218:219] neg_lo:[0,1] neg_hi:[0,1]
	v_pk_add_f32 v[224:225], v[224:225], v[220:221] neg_lo:[0,1] neg_hi:[0,1]
	v_pk_fma_f32 v[210:211], v[62:63], v[222:223], v[218:219]
	v_pk_fma_f32 v[212:213], v[64:65], v[224:225], v[220:221]
	v_lshlrev_b32_e32 v218, 16, v158
	v_and_b32_e32 v219, 0xffff0000, v158
	v_lshlrev_b32_e32 v220, 16, v159
	v_and_b32_e32 v221, 0xffff0000, v159
	v_lshlrev_b32_e32 v222, 16, v160
	v_and_b32_e32 v223, 0xffff0000, v160
	v_lshlrev_b32_e32 v224, 16, v161
	v_and_b32_e32 v225, 0xffff0000, v161
	v_lshlrev_b32_e32 v228, 16, v162
	v_and_b32_e32 v229, 0xffff0000, v162
	v_lshlrev_b32_e32 v230, 16, v163
	v_and_b32_e32 v231, 0xffff0000, v163
	v_pk_mul_f32 v[222:223], v[222:223], v[100:101] op_sel_hi:[1,0]
	v_pk_mul_f32 v[224:225], v[224:225], v[100:101] op_sel_hi:[1,0]
	v_pk_fma_f32 v[222:223], v[228:229], v[100:101], v[222:223] op_sel:[0,1,0] op_sel_hi:[1,1,1]
	v_pk_fma_f32 v[224:225], v[230:231], v[100:101], v[224:225] op_sel:[0,1,0] op_sel_hi:[1,1,1]
	v_pk_add_f32 v[222:223], v[222:223], v[218:219] neg_lo:[0,1] neg_hi:[0,1]
	v_pk_add_f32 v[224:225], v[224:225], v[220:221] neg_lo:[0,1] neg_hi:[0,1]
	v_pk_fma_f32 v[214:215], v[66:67], v[222:223], v[218:219]
	v_pk_fma_f32 v[216:217], v[68:69], v[224:225], v[220:221]
	v_lshlrev_b32_e32 v228, 16, v164
	v_and_b32_e32 v229, 0xffff0000, v164
	v_lshlrev_b32_e32 v230, 16, v165
	v_and_b32_e32 v231, 0xffff0000, v165
	v_lshlrev_b32_e32 v232, 16, v166
	v_and_b32_e32 v233, 0xffff0000, v166
	v_lshlrev_b32_e32 v234, 16, v167
	v_and_b32_e32 v235, 0xffff0000, v167
	v_pk_add_f32 v[228:229], v[228:229], -1.0 op_sel_hi:[1,0]
	v_pk_add_f32 v[230:231], v[230:231], -1.0 op_sel_hi:[1,0]
	v_pk_fma_f32 v[228:229], v[228:229], v[70:71], 1.0 op_sel_hi:[1,1,0]
	v_pk_fma_f32 v[230:231], v[230:231], v[72:73], 1.0 op_sel_hi:[1,1,0]
	v_pk_add_f32 v[232:233], v[232:233], -1.0 op_sel_hi:[1,0]
	v_pk_add_f32 v[234:235], v[234:235], -1.0 op_sel_hi:[1,0]
	v_pk_fma_f32 v[232:233], v[232:233], v[70:71], 1.0 op_sel_hi:[1,1,0]
	v_pk_fma_f32 v[234:235], v[234:235], v[72:73], 1.0 op_sel_hi:[1,1,0]
	v_pk_mul_f32 v[228:229], v[210:211], v[228:229]
	v_pk_mul_f32 v[230:231], v[212:213], v[230:231]
	v_pk_fma_f32 v[228:229], v[210:211], v[232:233], v[228:229]
	v_pk_fma_f32 v[230:231], v[212:213], v[234:235], v[230:231]
	v_pk_mul_f32 v[228:229], v[206:207], v[228:229]
	v_pk_mul_f32 v[230:231], v[208:209], v[230:231]
	v_pk_mul_f32 v[236:237], v[228:229], v[74:75]
	v_pk_fma_f32 v[236:237], v[230:231], v[76:77], v[236:237]
	v_add_f32_e32 v236, v236, v237
	s_nop 1
	v_add_f32_dpp v236, v236, v236 row_ror:8 row_mask:0xf bank_mask:0xf bound_ctrl:1
	s_nop 1
	v_add_f32_dpp v236, v236, v236 row_ror:4 row_mask:0xf bank_mask:0xf bound_ctrl:1
	s_nop 1
	v_add_f32_dpp v236, v236, v236 row_ror:2 row_mask:0xf bank_mask:0xf bound_ctrl:1
	s_nop 1
	v_add_f32_dpp v236, v236, v236 row_ror:1 row_mask:0xf bank_mask:0xf bound_ctrl:1
	v_lshlrev_b32_e32 v232, 16, v168
	v_and_b32_e32 v233, 0xffff0000, v168
	v_lshlrev_b32_e32 v234, 16, v169
	v_and_b32_e32 v235, 0xffff0000, v169
	v_pk_mul_f32 v[202:203], v[202:203], v[102:103] op_sel:[0,1] op_sel_hi:[1,1]
	v_pk_mul_f32 v[204:205], v[204:205], v[102:103] op_sel:[0,1] op_sel_hi:[1,1]
	v_pk_fma_f32 v[202:203], v[202:203], v[78:79], v[82:83]
	v_pk_fma_f32 v[204:205], v[204:205], v[80:81], v[84:85]
	v_pk_fma_f32 v[202:203], v[236:237], v[214:215], v[202:203] op_sel_hi:[0,1,1]
	v_pk_fma_f32 v[204:205], v[236:237], v[216:217], v[204:205] op_sel_hi:[0,1,1]
	v_pk_mul_f32 v[202:203], v[202:203], v[232:233]
	v_pk_mul_f32 v[204:205], v[204:205], v[234:235]
	v_add_f32_dpp v238, v238, v238 row_ror:8 row_mask:0xf bank_mask:0xf bound_ctrl:1
	s_nop 1
	v_add_f32_dpp v238, v238, v238 row_ror:4 row_mask:0xf bank_mask:0xf bound_ctrl:1
	s_nop 1
	v_add_f32_dpp v238, v238, v238 row_ror:2 row_mask:0xf bank_mask:0xf bound_ctrl:1
	s_nop 1
	v_add_f32_dpp v238, v238, v238 row_ror:1 row_mask:0xf bank_mask:0xf bound_ctrl:1
	s_nop 0
	v_readlane_b32 s10, v238, 0
	v_readlane_b32 s11, v238, 16
	v_readlane_b32 s12, v238, 32
	v_readlane_b32 s13, v238, 48
	v_mov_b32_e32 v236, s10
	v_add_f32_e32 v236, s11, v236
	v_add_f32_e32 v236, s12, v236
	v_add_f32_e32 v236, s13, v236
	v_mov_b32_e32 v104, 0x3727c5ac
	v_fmac_f32_e32 v104, 0x3b2aaaab, v236
	v_rsq_f32_e32 v104, v104
	s_nop 0
	v_pk_mul_f32 v[194:195], v[194:195], v[104:105] op_sel_hi:[1,0]
	v_pk_mul_f32 v[198:199], v[198:199], v[104:105] op_sel_hi:[1,0]
	v_pk_mul_f32 v[200:201], v[200:201], v[104:105] op_sel_hi:[1,0]
	v_pk_mul_f32 v[194:195], v[194:195], v[46:47]
	v_pk_mul_f32 v[198:199], v[198:199], v[48:49]
	v_pk_mul_f32 v[200:201], v[200:201], v[50:51]
	v_cvt_pk_bf16_f32 v242, v194, v195
	v_cvt_pk_bf16_f32 v243, v198, v199
	v_cvt_pk_bf16_f32 v244, v200, v201
	v_mad_u64_u32 v[106:107], vcc, v97, v96, v[90:91]
	global_store_dwordx3 v[106:107], v[242:244], off
	v_cvt_pk_bf16_f32 v102, v202, v203
	v_cvt_pk_bf16_f32 v103, v204, v205
	v_mad_u64_u32 v[108:109], vcc, v97, v96, v[92:93]
	global_store_dwordx2 v[108:109], v[102:103], off offset:768
	s_add_u32 s6, s6, s20
	s_cmp_lt_u32 s6, s21
	s_cbranch_scc1 .Lcb7_top
	s_branch .LBB0_1351

.Lcb18_entry:
	s_waitcnt vmcnt(0) lgkmcnt(0)
	v_readlane_b32 s98, v246, 10
	v_readlane_b32 s99, v246, 11
	s_nop 4
	v_and_b32_e32 v0, 63, v226
	v_mul_u32_u24_e32 v2, 12, v0
	v_mul_u32_u24_e32 v4, 24, v0
	v_lshlrev_b32_e32 v6, 3, v0
	v_lshlrev_b32_e32 v8, 4, v0
	v_mov_b32_e32 v3, 0
	v_mov_b32_e32 v5, 0
	v_mov_b32_e32 v7, 0
	v_mov_b32_e32 v9, 0
	s_load_dwordx2 s[100:101], s[98:99], 0x68
	s_waitcnt lgkmcnt(0)
	s_add_u32 s100, s100, 0x3200
	s_addc_u32 s101, s101, 0
	global_load_dwordx2 v[10:11], v4, s[100:101] offset:0
	global_load_dwordx2 v[12:13], v4, s[100:101] offset:8
	global_load_dwordx2 v[14:15], v4, s[100:101] offset:16
	s_load_dwordx2 s[100:101], s[98:99], 0x68
	s_waitcnt lgkmcnt(0)
	s_add_u32 s100, s100, 0x3c00
	s_addc_u32 s101, s101, 0
	global_load_dwordx2 v[16:17], v4, s[100:101] offset:0
	global_load_dwordx2 v[18:19], v4, s[100:101] offset:8
	global_load_dwordx2 v[20:21], v4, s[100:101] offset:16
	s_load_dwordx2 s[100:101], s[98:99], 0x68
	s_waitcnt lgkmcnt(0)
	s_add_u32 s100, s100, 0x4600
	s_addc_u32 s101, s101, 0
	global_load_dwordx2 v[22:23], v4, s[100:101] offset:0
	global_load_dwordx2 v[24:25], v4, s[100:101] offset:8
	global_load_dwordx2 v[26:27], v4, s[100:101] offset:16
	s_load_dwordx2 s[100:101], s[98:99], 0x68
	s_waitcnt lgkmcnt(0)
	s_add_u32 s100, s100, 0x5000
	s_addc_u32 s101, s101, 0
	global_load_dwordx2 v[28:29], v4, s[100:101] offset:0
	global_load_dwordx2 v[30:31], v4, s[100:101] offset:8
	global_load_dwordx2 v[32:33], v4, s[100:101] offset:16
	s_load_dwordx2 s[100:101], s[98:99], 0x68
	s_waitcnt lgkmcnt(0)
	s_add_u32 s100, s100, 0x5a00
	s_addc_u32 s101, s101, 0
	global_load_dwordx2 v[34:35], v4, s[100:101] offset:0
	global_load_dwordx2 v[36:37], v4, s[100:101] offset:8
	global_load_dwordx2 v[38:39], v4, s[100:101] offset:16
	s_load_dwordx2 s[100:101], s[98:99], 0x70
	s_waitcnt lgkmcnt(0)
	s_add_u32 s100, s100, 0xa00
	s_addc_u32 s101, s101, 0
	global_load_dwordx2 v[40:41], v4, s[100:101] offset:0
	global_load_dwordx2 v[42:43], v4, s[100:101] offset:8
	global_load_dwordx2 v[44:45], v4, s[100:101] offset:16
	s_load_dwordx2 s[100:101], s[98:99], 0x90
	s_waitcnt lgkmcnt(0)
	s_add_u32 s100, s100, 0x600
	s_addc_u32 s101, s101, 0
	global_load_dwordx2 v[46:47], v4, s[100:101] offset:0
	global_load_dwordx2 v[48:49], v4, s[100:101] offset:8
	global_load_dwordx2 v[50:51], v4, s[100:101] offset:16
	s_load_dwordx2 s[100:101], s[98:99], 0x88
	s_waitcnt lgkmcnt(0)
	s_add_u32 s100, s100, 0x18
	s_addc_u32 s101, s101, 0
	v_mad_u32_u24 v236, v0, 6, 0
	v_lshrrev_b32_e32 v236, 6, v236
	v_lshlrev_b32_e32 v236, 2, v236
	global_load_dword v52, v236, s[100:101]
	v_mad_u32_u24 v236, v0, 6, 1
	v_lshrrev_b32_e32 v236, 6, v236
	v_lshlrev_b32_e32 v236, 2, v236
	global_load_dword v53, v236, s[100:101]
	v_mad_u32_u24 v236, v0, 6, 2
	v_lshrrev_b32_e32 v236, 6, v236
	v_lshlrev_b32_e32 v236, 2, v236
	global_load_dword v54, v236, s[100:101]
	v_mad_u32_u24 v236, v0, 6, 3
	v_lshrrev_b32_e32 v236, 6, v236
	v_lshlrev_b32_e32 v236, 2, v236
	global_load_dword v55, v236, s[100:101]
	v_mad_u32_u24 v236, v0, 6, 4
	v_lshrrev_b32_e32 v236, 6, v236
	v_lshlrev_b32_e32 v236, 2, v236
	global_load_dword v56, v236, s[100:101]
	v_mad_u32_u24 v236, v0, 6, 5
	v_lshrrev_b32_e32 v236, 6, v236
	v_lshlrev_b32_e32 v236, 2, v236
	global_load_dword v57, v236, s[100:101]
	s_load_dwordx2 s[100:101], s[98:99], 0x98
	s_waitcnt lgkmcnt(0)
	s_add_u32 s100, s100, 0x1000
	s_addc_u32 s101, s101, 0
	global_load_dwordx2 v[58:59], v8, s[100:101] offset:0
	global_load_dwordx2 v[60:61], v8, s[100:101] offset:8
	s_load_dwordx2 s[100:101], s[98:99], 0x98
	s_waitcnt lgkmcnt(0)
	s_add_u32 s100, s100, 0x1400
	s_addc_u32 s101, s101, 0
	global_load_dwordx2 v[62:63], v8, s[100:101] offset:0
	global_load_dwordx2 v[64:65], v8, s[100:101] offset:8
	s_load_dwordx2 s[100:101], s[98:99], 0x98
	s_waitcnt lgkmcnt(0)
	s_add_u32 s100, s100, 0x1800
	s_addc_u32 s101, s101, 0
	global_load_dwordx2 v[66:67], v8, s[100:101] offset:0
	global_load_dwordx2 v[68:69], v8, s[100:101] offset:8
	s_load_dwordx2 s[100:101], s[98:99], 0xd0
	s_waitcnt lgkmcnt(0)
	s_add_u32 s100, s100, 0x400
	s_addc_u32 s101, s101, 0
	global_load_dwordx2 v[70:71], v8, s[100:101] offset:0
	global_load_dwordx2 v[72:73], v8, s[100:101] offset:8
	s_load_dwordx2 s[100:101], s[98:99], 0xd8
	s_waitcnt lgkmcnt(0)
	s_add_u32 s100, s100, 0x400
	s_addc_u32 s101, s101, 0
	global_load_dwordx2 v[74:75], v8, s[100:101] offset:0
	global_load_dwordx2 v[76:77], v8, s[100:101] offset:8
	s_load_dwordx2 s[100:101], s[98:99], 0xe0
	s_waitcnt lgkmcnt(0)
	s_add_u32 s100, s100, 0x400
	s_addc_u32 s101, s101, 0
	global_load_dwordx2 v[78:79], v8, s[100:101] offset:0
	global_load_dwordx2 v[80:81], v8, s[100:101] offset:8
	s_load_dwordx2 s[100:101], s[98:99], 0xe8
	s_waitcnt lgkmcnt(0)
	s_add_u32 s100, s100, 0x400
	s_addc_u32 s101, s101, 0
	global_load_dwordx2 v[82:83], v8, s[100:101] offset:0
	global_load_dwordx2 v[84:85], v8, s[100:101] offset:8
	s_load_dwordx2 s[100:101], s[98:99], 0x178
	s_waitcnt lgkmcnt(0)
	v_mov_b32_e32 v86, s100
	v_mov_b32_e32 v87, s101
	v_lshl_add_u64 v[86:87], v[86:87], 0, v[2:3]
	s_load_dwordx2 s[100:101], s[98:99], 0x178
	s_waitcnt lgkmcnt(0)
	s_add_u32 s100, s100, 0xd20
	s_addc_u32 s101, s101, 0
	v_mov_b32_e32 v88, s100
	v_mov_b32_e32 v89, s101
	v_lshl_add_u64 v[88:89], v[88:89], 0, v[6:7]
	s_load_dwordx2 s[100:101], s[98:99], 0x198
	s_waitcnt lgkmcnt(0)
	v_mov_b32_e32 v90, s100
	v_mov_b32_e32 v91, s101
	v_lshl_add_u64 v[90:91], v[90:91], 0, v[2:3]
	s_load_dwordx2 s[100:101], s[98:99], 0x198
	s_waitcnt lgkmcnt(0)
	v_mov_b32_e32 v92, s100
	v_mov_b32_e32 v93, s101
	v_lshl_add_u64 v[92:93], v[92:93], 0, v[6:7]
	s_load_dwordx2 s[100:101], s[98:99], 0x188
	s_waitcnt lgkmcnt(0)
	v_mov_b32_e32 v94, s100
	v_mov_b32_e32 v95, s101
	v_lshl_add_u64 v[94:95], v[94:95], 0, v[6:7]
	v_mov_b32_e32 v1, 0x1520
	v_mov_b32_e32 v96, 0xa00
	v_mov_b32_e32 v98, 0xbfb8aa3b
	v_readfirstlane_b32 s6, v204
	s_waitcnt vmcnt(0)
	s_nop 3
	s_mov_b32 s20, s3
	s_movk_i32 s21, 0x5000
	s_cmp_eq_u32 s3, 0x800
	s_cbranch_scc0 .Lcb18_top
	s_mul_i32 s6, s6, 10
	s_mov_b32 s20, 1
	s_add_u32 s21, s6, 10

.Lcb18_skip4:
	v_pk_mul_f32 v[176:177], v[170:171], v[98:99] op_sel_hi:[1,0]
	v_pk_mul_f32 v[178:179], v[172:173], v[98:99] op_sel_hi:[1,0]
	v_pk_mul_f32 v[180:181], v[174:175], v[98:99] op_sel_hi:[1,0]
	v_exp_f32_e32 v176, v176
	v_exp_f32_e32 v177, v177
	v_exp_f32_e32 v178, v178
	v_exp_f32_e32 v179, v179
	v_exp_f32_e32 v180, v180
	v_exp_f32_e32 v181, v181
	v_pk_add_f32 v[176:177], v[176:177], 1.0 op_sel_hi:[1,0]
	v_pk_add_f32 v[178:179], v[178:179], 1.0 op_sel_hi:[1,0]
	v_pk_add_f32 v[180:181], v[180:181], 1.0 op_sel_hi:[1,0]
	v_rcp_f32_e32 v176, v176
	v_rcp_f32_e32 v177, v177
	v_rcp_f32_e32 v178, v178
	v_rcp_f32_e32 v179, v179
	v_rcp_f32_e32 v180, v180
	v_rcp_f32_e32 v181, v181
	v_pk_mul_f32 v[170:171], v[170:171], v[176:177]
	v_pk_mul_f32 v[172:173], v[172:173], v[178:179]
	v_pk_mul_f32 v[174:175], v[174:175], v[180:181]
	v_lshlrev_b32_e32 v182, 16, v130
	v_and_b32_e32 v183, 0xffff0000, v130
	v_lshlrev_b32_e32 v184, 16, v131
	v_and_b32_e32 v185, 0xffff0000, v131
	v_lshlrev_b32_e32 v186, 16, v132
	v_and_b32_e32 v187, 0xffff0000, v132
	v_pk_mul_f32 v[176:177], v[182:183], v[98:99] op_sel_hi:[1,0]
	v_pk_mul_f32 v[178:179], v[184:185], v[98:99] op_sel_hi:[1,0]
	v_pk_mul_f32 v[180:181], v[186:187], v[98:99] op_sel_hi:[1,0]
	v_exp_f32_e32 v176, v176
	v_exp_f32_e32 v177, v177
	v_exp_f32_e32 v178, v178
	v_exp_f32_e32 v179, v179
	v_exp_f32_e32 v180, v180
	v_exp_f32_e32 v181, v181
	v_pk_add_f32 v[176:177], v[176:177], 1.0 op_sel_hi:[1,0]
	v_pk_add_f32 v[178:179], v[178:179], 1.0 op_sel_hi:[1,0]
	v_pk_add_f32 v[180:181], v[180:181], 1.0 op_sel_hi:[1,0]
	v_rcp_f32_e32 v176, v176
	v_rcp_f32_e32 v177, v177
	v_rcp_f32_e32 v178, v178
	v_rcp_f32_e32 v179, v179
	v_rcp_f32_e32 v180, v180
	v_rcp_f32_e32 v181, v181
	v_pk_mul_f32 v[188:189], v[182:183], v[176:177]
	v_pk_mul_f32 v[190:191], v[184:185], v[178:179]
	v_pk_mul_f32 v[192:193], v[186:187], v[180:181]
	v_lshlrev_b32_e32 v176, 16, v134
	v_and_b32_e32 v177, 0xffff0000, v134
	v_lshlrev_b32_e32 v178, 16, v135
	v_and_b32_e32 v179, 0xffff0000, v135
	v_lshlrev_b32_e32 v180, 16, v136
	v_and_b32_e32 v181, 0xffff0000, v136
	v_lshlrev_b32_e32 v182, 16, v138
	v_and_b32_e32 v183, 0xffff0000, v138
	v_lshlrev_b32_e32 v184, 16, v139
	v_and_b32_e32 v185, 0xffff0000, v139
	v_lshlrev_b32_e32 v186, 16, v140
	v_and_b32_e32 v187, 0xffff0000, v140
	v_pk_add_f32 v[194:195], v[176:177], v[182:183]
	v_pk_add_f32 v[196:197], v[178:179], v[184:185]
	v_pk_add_f32 v[198:199], v[180:181], v[186:187]
	v_pk_fma_f32 v[194:195], v[52:53], v[170:171], v[194:195]
	v_pk_fma_f32 v[196:197], v[54:55], v[172:173], v[196:197]
	v_pk_fma_f32 v[198:199], v[56:57], v[174:175], v[198:199]
	v_pk_mul_f32 v[194:195], v[194:195], v[188:189]
	v_pk_mul_f32 v[196:197], v[196:197], v[190:191]
	v_pk_mul_f32 v[198:199], v[198:199], v[192:193]
	v_pk_mul_f32 v[238:239], v[194:195], v[194:195]
	v_pk_fma_f32 v[238:239], v[196:197], v[196:197], v[238:239]
	v_pk_fma_f32 v[238:239], v[198:199], v[198:199], v[238:239]
	v_add_f32_e32 v238, v238, v239
	s_waitcnt vmcnt(0)
	v_lshlrev_b32_e32 v200, 16, v142
	v_and_b32_e32 v201, 0xffff0000, v142
	v_lshlrev_b32_e32 v202, 16, v143
	v_and_b32_e32 v203, 0xffff0000, v143
	v_lshlrev_b32_e32 v218, 16, v144
	v_and_b32_e32 v219, 0xffff0000, v144
	v_lshlrev_b32_e32 v220, 16, v145
	v_and_b32_e32 v221, 0xffff0000, v145
	v_pk_add_f32 v[200:201], v[200:201], v[218:219]
	v_pk_add_f32 v[202:203], v[202:203], v[220:221]
	v_pk_add_f32 v[236:237], v[200:201], v[202:203]
	v_add_f32_e32 v236, v236, v237
	s_nop 1
	v_add_f32_dpp v236, v236, v236 row_ror:8 row_mask:0xf bank_mask:0xf bound_ctrl:1
	s_nop 1
	v_add_f32_dpp v236, v236, v236 row_ror:4 row_mask:0xf bank_mask:0xf bound_ctrl:1
	s_nop 1
	v_add_f32_dpp v236, v236, v236 row_ror:2 row_mask:0xf bank_mask:0xf bound_ctrl:1
	s_nop 1
	v_add_f32_dpp v236, v236, v236 row_ror:1 row_mask:0xf bank_mask:0xf bound_ctrl:1
	v_mul_f32_e32 v102, 0x3c800000, v236
	v_pk_add_f32 v[200:201], v[200:201], v[102:103] op_sel_hi:[1,0] neg_lo:[0,1] neg_hi:[0,1]
	v_pk_add_f32 v[202:203], v[202:203], v[102:103] op_sel_hi:[1,0] neg_lo:[0,1] neg_hi:[0,1]
	v_pk_mul_f32 v[236:237], v[200:201], v[200:201]
	v_pk_fma_f32 v[236:237], v[202:203], v[202:203], v[236:237]
	v_add_f32_e32 v236, v236, v237
	s_nop 1
	v_add_f32_dpp v236, v236, v236 row_ror:8 row_mask:0xf bank_mask:0xf bound_ctrl:1
	s_nop 1
	v_add_f32_dpp v236, v236, v236 row_ror:4 row_mask:0xf bank_mask:0xf bound_ctrl:1
	s_nop 1
	v_add_f32_dpp v236, v236, v236 row_ror:2 row_mask:0xf bank_mask:0xf bound_ctrl:1
	s_nop 1
	v_add_f32_dpp v236, v236, v236 row_ror:1 row_mask:0xf bank_mask:0xf bound_ctrl:1
	v_mov_b32_e32 v104, 0x3a27c5ac
	v_fmac_f32_e32 v104, 0x3c800000, v236
	v_rsq_f32_e32 v103, v104
	v_lshlrev_b32_e32 v218, 16, v146
	v_and_b32_e32 v219, 0xffff0000, v146
	v_lshlrev_b32_e32 v220, 16, v147
	v_and_b32_e32 v221, 0xffff0000, v147
	v_lshlrev_b32_e32 v222, 16, v148
	v_and_b32_e32 v223, 0xffff0000, v148
	v_lshlrev_b32_e32 v224, 16, v149
	v_and_b32_e32 v225, 0xffff0000, v149
	v_lshlrev_b32_e32 v228, 16, v150
	v_and_b32_e32 v229, 0xffff0000, v150
	v_lshlrev_b32_e32 v230, 16, v151
	v_and_b32_e32 v231, 0xffff0000, v151
	v_pk_mul_f32 v[222:223], v[222:223], v[100:101] op_sel_hi:[1,0]
	v_pk_mul_f32 v[224:225], v[224:225], v[100:101] op_sel_hi:[1,0]
	v_pk_fma_f32 v[222:223], v[228:229], v[100:101], v[222:223] op_sel:[0,1,0] op_sel_hi:[1,1,1]
	v_pk_fma_f32 v[224:225], v[230:231], v[100:101], v[224:225] op_sel:[0,1,0] op_sel_hi:[1,1,1]
	v_pk_add_f32 v[222:223], v[222:223], v[218:219] neg_lo:[0,1] neg_hi:[0,1]
	v_pk_add_f32 v[224:225], v[224:225], v[220:221] neg_lo:[0,1] neg_hi:[0,1]
	v_pk_fma_f32 v[206:207], v[58:59], v[222:223], v[218:219]
	v_pk_fma_f32 v[208:209], v[60:61], v[224:225], v[220:221]
	v_lshlrev_b32_e32 v218, 16, v152
	v_and_b32_e32 v219, 0xffff0000, v152
	v_lshlrev_b32_e32 v220, 16, v153
	v_and_b32_e32 v221, 0xffff0000, v153
	v_lshlrev_b32_e32 v222, 16, v154
	v_and_b32_e32 v223, 0xffff0000, v154
	v_lshlrev_b32_e32 v224, 16, v155
	v_and_b32_e32 v225, 0xffff0000, v155
	v_lshlrev_b32_e32 v228, 16, v156
	v_and_b32_e32 v229, 0xffff0000, v156
	v_lshlrev_b32_e32 v230, 16, v157
	v_and_b32_e32 v231, 0xffff0000, v157
	v_pk_mul_f32 v[222:223], v[222:223], v[100:101] op_sel_hi:[1,0]
	v_pk_mul_f32 v[224:225], v[224:225], v[100:101] op_sel_hi:[1,0]
	v_pk_fma_f32 v[222:223], v[228:229], v[100:101], v[222:223] op_sel:[0,1,0] op_sel_hi:[1,1,1]
	v_pk_fma_f32 v[224:225], v[230:231], v[100:101], v[224:225] op_sel:[0,1,0] op_sel_hi:[1,1,1]
	v_pk_add_f32 v[222:223], v[222:223], v[218:219] neg_lo:[0,1] neg_hi:[0,1]
	v_pk_add_f32 v[224:225], v[224:225], v[220:221] neg_lo:[0,1] neg_hi:[0,1]
	v_pk_fma_f32 v[210:211], v[62:63], v[222:223], v[218:219]
	v_pk_fma_f32 v[212:213], v[64:65], v[224:225], v[220:221]
	v_lshlrev_b32_e32 v218, 16, v158
	v_and_b32_e32 v219, 0xffff0000, v158
	v_lshlrev_b32_e32 v220, 16, v159
	v_and_b32_e32 v221, 0xffff0000, v159
	v_lshlrev_b32_e32 v222, 16, v160
	v_and_b32_e32 v223, 0xffff0000, v160
	v_lshlrev_b32_e32 v224, 16, v161
	v_and_b32_e32 v225, 0xffff0000, v161
	v_lshlrev_b32_e32 v228, 16, v162
	v_and_b32_e32 v229, 0xffff0000, v162
	v_lshlrev_b32_e32 v230, 16, v163
	v_and_b32_e32 v231, 0xffff0000, v163
	v_pk_mul_f32 v[222:223], v[222:223], v[100:101] op_sel_hi:[1,0]
	v_pk_mul_f32 v[224:225], v[224:225], v[100:101] op_sel_hi:[1,0]
	v_pk_fma_f32 v[222:223], v[228:229], v[100:101], v[222:223] op_sel:[0,1,0] op_sel_hi:[1,1,1]
	v_pk_fma_f32 v[224:225], v[230:231], v[100:101], v[224:225] op_sel:[0,1,0] op_sel_hi:[1,1,1]
	v_pk_add_f32 v[222:223], v[222:223], v[218:219] neg_lo:[0,1] neg_hi:[0,1]
	v_pk_add_f32 v[224:225], v[224:225], v[220:221] neg_lo:[0,1] neg_hi:[0,1]
	v_pk_fma_f32 v[214:215], v[66:67], v[222:223], v[218:219]
	v_pk_fma_f32 v[216:217], v[68:69], v[224:225], v[220:221]
	v_lshlrev_b32_e32 v228, 16, v164
	v_and_b32_e32 v229, 0xffff0000, v164
	v_lshlrev_b32_e32 v230, 16, v165
	v_and_b32_e32 v231, 0xffff0000, v165
	v_lshlrev_b32_e32 v232, 16, v166
	v_and_b32_e32 v233, 0xffff0000, v166
	v_lshlrev_b32_e32 v234, 16, v167
	v_and_b32_e32 v235, 0xffff0000, v167
	v_pk_add_f32 v[228:229], v[228:229], -1.0 op_sel_hi:[1,0]
	v_pk_add_f32 v[230:231], v[230:231], -1.0 op_sel_hi:[1,0]
	v_pk_fma_f32 v[228:229], v[228:229], v[70:71], 1.0 op_sel_hi:[1,1,0]
	v_pk_fma_f32 v[230:231], v[230:231], v[72:73], 1.0 op_sel_hi:[1,1,0]
	v_pk_add_f32 v[232:233], v[232:233], -1.0 op_sel_hi:[1,0]
	v_pk_add_f32 v[234:235], v[234:235], -1.0 op_sel_hi:[1,0]
	v_pk_fma_f32 v[232:233], v[232:233], v[70:71], 1.0 op_sel_hi:[1,1,0]
	v_pk_fma_f32 v[234:235], v[234:235], v[72:73], 1.0 op_sel_hi:[1,1,0]
	v_pk_mul_f32 v[228:229], v[210:211], v[228:229]
	v_pk_mul_f32 v[230:231], v[212:213], v[230:231]
	v_pk_fma_f32 v[228:229], v[210:211], v[232:233], v[228:229]
	v_pk_fma_f32 v[230:231], v[212:213], v[234:235], v[230:231]
	v_pk_mul_f32 v[228:229], v[206:207], v[228:229]
	v_pk_mul_f32 v[230:231], v[208:209], v[230:231]
	v_pk_mul_f32 v[236:237], v[228:229], v[74:75]
	v_pk_fma_f32 v[236:237], v[230:231], v[76:77], v[236:237]
	v_add_f32_e32 v236, v236, v237
	s_nop 1
	v_add_f32_dpp v236, v236, v236 row_ror:8 row_mask:0xf bank_mask:0xf bound_ctrl:1
	s_nop 1
	v_add_f32_dpp v236, v236, v236 row_ror:4 row_mask:0xf bank_mask:0xf bound_ctrl:1
	s_nop 1
	v_add_f32_dpp v236, v236, v236 row_ror:2 row_mask:0xf bank_mask:0xf bound_ctrl:1
	s_nop 1
	v_add_f32_dpp v236, v236, v236 row_ror:1 row_mask:0xf bank_mask:0xf bound_ctrl:1
	v_lshlrev_b32_e32 v232, 16, v168
	v_and_b32_e32 v233, 0xffff0000, v168
	v_lshlrev_b32_e32 v234, 16, v169
	v_and_b32_e32 v235, 0xffff0000, v169
	v_pk_mul_f32 v[200:201], v[200:201], v[102:103] op_sel:[0,1] op_sel_hi:[1,1]
	v_pk_mul_f32 v[202:203], v[202:203], v[102:103] op_sel:[0,1] op_sel_hi:[1,1]
	v_pk_fma_f32 v[200:201], v[200:201], v[78:79], v[82:83]
	v_pk_fma_f32 v[202:203], v[202:203], v[80:81], v[84:85]
	v_pk_fma_f32 v[200:201], v[236:237], v[214:215], v[200:201] op_sel_hi:[0,1,1]
	v_pk_fma_f32 v[202:203], v[236:237], v[216:217], v[202:203] op_sel_hi:[0,1,1]
	v_pk_mul_f32 v[200:201], v[200:201], v[232:233]
	v_pk_mul_f32 v[202:203], v[202:203], v[234:235]
	v_add_f32_dpp v238, v238, v238 row_ror:8 row_mask:0xf bank_mask:0xf bound_ctrl:1
	s_nop 1
	v_add_f32_dpp v238, v238, v238 row_ror:4 row_mask:0xf bank_mask:0xf bound_ctrl:1
	s_nop 1
	v_add_f32_dpp v238, v238, v238 row_ror:2 row_mask:0xf bank_mask:0xf bound_ctrl:1
	s_nop 1
	v_add_f32_dpp v238, v238, v238 row_ror:1 row_mask:0xf bank_mask:0xf bound_ctrl:1
	s_nop 0
	v_readlane_b32 s10, v238, 0
	v_readlane_b32 s11, v238, 16
	v_readlane_b32 s12, v238, 32
	v_readlane_b32 s13, v238, 48
	v_mov_b32_e32 v236, s10
	v_add_f32_e32 v236, s11, v236
	v_add_f32_e32 v236, s12, v236
	v_add_f32_e32 v236, s13, v236
	v_mov_b32_e32 v104, 0x3727c5ac
	v_fmac_f32_e32 v104, 0x3b2aaaab, v236
	v_rsq_f32_e32 v104, v104
	s_nop 0
	v_pk_mul_f32 v[194:195], v[194:195], v[104:105] op_sel_hi:[1,0]
	v_pk_mul_f32 v[196:197], v[196:197], v[104:105] op_sel_hi:[1,0]
	v_pk_mul_f32 v[198:199], v[198:199], v[104:105] op_sel_hi:[1,0]
	v_pk_mul_f32 v[194:195], v[194:195], v[46:47]
	v_pk_mul_f32 v[196:197], v[196:197], v[48:49]
	v_pk_mul_f32 v[198:199], v[198:199], v[50:51]
	v_cvt_pk_bf16_f32 v242, v194, v195
	v_cvt_pk_bf16_f32 v243, v196, v197
	v_cvt_pk_bf16_f32 v244, v198, v199
	v_mad_u64_u32 v[106:107], vcc, v97, v96, v[90:91]
	global_store_dwordx3 v[106:107], v[242:244], off
	v_cvt_pk_bf16_f32 v102, v200, v201
	v_cvt_pk_bf16_f32 v103, v202, v203
	v_mad_u64_u32 v[108:109], vcc, v97, v96, v[92:93]
	global_store_dwordx2 v[108:109], v[102:103], off offset:768
	s_add_u32 s6, s6, s20
	s_cmp_lt_u32 s6, s21
	s_cbranch_scc1 .Lcb18_top
	s_branch .LBB0_2837
